# adds: hand-written GLA chunk scan loop with all 64 loads in flight
# speedup vs baseline: 1.0146x; 1.0063x over previous
.LBB0_362:
	s_lshr_b32 s0, s24, 6
	s_and_b32 s1, s24, 63
	s_lshl_b32 s18, s0, 14
	s_lshl_b32 s1, s1, 8
	s_add_i32 s1, s1, s18
	s_add_u32 s18, s2, s1
	s_addc_u32 s19, s14, 0
	s_lshl_b32 s25, s0, 8
	s_add_u32 s6, s10, s25
	s_addc_u32 s7, s11, 0
	s_add_u32 s6, s6, 0x1a800000
	s_addc_u32 s7, s7, 0
	v_lshrrev_b32_e32 v80, 7, v204
	v_and_b32_e32 v81, 63, v10
	v_lshlrev_b32_e32 v78, 21, v80
	v_lshlrev_b32_e32 v79, 15, v80
	v_lshl_add_u32 v78, v10, 1, v78
	v_lshl_add_u32 v79, v81, 2, v79
	global_load_ushort v14, v78, s[18:19] nt
	s_add_u32 s36, s18, 0x10000
	s_addc_u32 s37, s19, 0
	global_load_ushort v15, v78, s[36:37] nt
	s_add_u32 s36, s18, 0x20000
	s_addc_u32 s37, s19, 0
	global_load_ushort v16, v78, s[36:37] nt
	s_add_u32 s36, s18, 0x30000
	s_addc_u32 s37, s19, 0
	global_load_ushort v17, v78, s[36:37] nt
	s_add_u32 s36, s18, 0x40000
	s_addc_u32 s37, s19, 0
	global_load_ushort v18, v78, s[36:37] nt
	s_add_u32 s36, s18, 0x50000
	s_addc_u32 s37, s19, 0
	global_load_ushort v19, v78, s[36:37] nt
	s_add_u32 s36, s18, 0x60000
	s_addc_u32 s37, s19, 0
	global_load_ushort v20, v78, s[36:37] nt
	s_add_u32 s36, s18, 0x70000
	s_addc_u32 s37, s19, 0
	global_load_ushort v21, v78, s[36:37] nt
	s_add_u32 s36, s18, 0x80000
	s_addc_u32 s37, s19, 0
	global_load_ushort v22, v78, s[36:37] nt
	s_add_u32 s36, s18, 0x90000
	s_addc_u32 s37, s19, 0
	global_load_ushort v23, v78, s[36:37] nt
	s_add_u32 s36, s18, 0xa0000
	s_addc_u32 s37, s19, 0
	global_load_ushort v24, v78, s[36:37] nt
	s_add_u32 s36, s18, 0xb0000
	s_addc_u32 s37, s19, 0
	global_load_ushort v25, v78, s[36:37] nt
	s_add_u32 s36, s18, 0xc0000
	s_addc_u32 s37, s19, 0
	global_load_ushort v26, v78, s[36:37] nt
	s_add_u32 s36, s18, 0xd0000
	s_addc_u32 s37, s19, 0
	global_load_ushort v27, v78, s[36:37] nt
	s_add_u32 s36, s18, 0xe0000
	s_addc_u32 s37, s19, 0
	global_load_ushort v28, v78, s[36:37] nt
	s_add_u32 s36, s18, 0xf0000
	s_addc_u32 s37, s19, 0
	global_load_ushort v29, v78, s[36:37] nt
	s_add_u32 s36, s18, 0x100000
	s_addc_u32 s37, s19, 0
	global_load_ushort v30, v78, s[36:37] nt
	s_add_u32 s36, s18, 0x110000
	s_addc_u32 s37, s19, 0
	global_load_ushort v31, v78, s[36:37] nt
	s_add_u32 s36, s18, 0x120000
	s_addc_u32 s37, s19, 0
	global_load_ushort v32, v78, s[36:37] nt
	s_add_u32 s36, s18, 0x130000
	s_addc_u32 s37, s19, 0
	global_load_ushort v33, v78, s[36:37] nt
	s_add_u32 s36, s18, 0x140000
	s_addc_u32 s37, s19, 0
	global_load_ushort v34, v78, s[36:37] nt
	s_add_u32 s36, s18, 0x150000
	s_addc_u32 s37, s19, 0
	global_load_ushort v35, v78, s[36:37] nt
	s_add_u32 s36, s18, 0x160000
	s_addc_u32 s37, s19, 0
	global_load_ushort v36, v78, s[36:37] nt
	s_add_u32 s36, s18, 0x170000
	s_addc_u32 s37, s19, 0
	global_load_ushort v37, v78, s[36:37] nt
	s_add_u32 s36, s18, 0x180000
	s_addc_u32 s37, s19, 0
	global_load_ushort v38, v78, s[36:37] nt
	s_add_u32 s36, s18, 0x190000
	s_addc_u32 s37, s19, 0
	global_load_ushort v39, v78, s[36:37] nt
	s_add_u32 s36, s18, 0x1a0000
	s_addc_u32 s37, s19, 0
	global_load_ushort v40, v78, s[36:37] nt
	s_add_u32 s36, s18, 0x1b0000
	s_addc_u32 s37, s19, 0
	global_load_ushort v41, v78, s[36:37] nt
	s_add_u32 s36, s18, 0x1c0000
	s_addc_u32 s37, s19, 0
	global_load_ushort v42, v78, s[36:37] nt
	s_add_u32 s36, s18, 0x1d0000
	s_addc_u32 s37, s19, 0
	global_load_ushort v43, v78, s[36:37] nt
	s_add_u32 s36, s18, 0x1e0000
	s_addc_u32 s37, s19, 0
	global_load_ushort v44, v78, s[36:37] nt
	s_add_u32 s36, s18, 0x1f0000
	s_addc_u32 s37, s19, 0
	global_load_ushort v45, v78, s[36:37] nt
	global_load_dword v46, v79, s[6:7]
	global_load_dword v47, v79, s[6:7] offset:1024
	global_load_dword v48, v79, s[6:7] offset:2048
	global_load_dword v49, v79, s[6:7] offset:3072
	s_add_u32 s36, s6, 0x1000
	s_addc_u32 s37, s7, 0
	global_load_dword v50, v79, s[36:37]
	global_load_dword v51, v79, s[36:37] offset:1024
	global_load_dword v52, v79, s[36:37] offset:2048
	global_load_dword v53, v79, s[36:37] offset:3072
	s_add_u32 s36, s6, 0x2000
	s_addc_u32 s37, s7, 0
	global_load_dword v54, v79, s[36:37]
	global_load_dword v55, v79, s[36:37] offset:1024
	global_load_dword v56, v79, s[36:37] offset:2048
	global_load_dword v57, v79, s[36:37] offset:3072
	s_add_u32 s36, s6, 0x3000
	s_addc_u32 s37, s7, 0
	global_load_dword v58, v79, s[36:37]
	global_load_dword v59, v79, s[36:37] offset:1024
	global_load_dword v60, v79, s[36:37] offset:2048
	global_load_dword v61, v79, s[36:37] offset:3072
	s_add_u32 s36, s6, 0x4000
	s_addc_u32 s37, s7, 0
	global_load_dword v62, v79, s[36:37]
	global_load_dword v63, v79, s[36:37] offset:1024
	global_load_dword v64, v79, s[36:37] offset:2048
	global_load_dword v65, v79, s[36:37] offset:3072
	s_add_u32 s36, s6, 0x5000
	s_addc_u32 s37, s7, 0
	global_load_dword v66, v79, s[36:37]
	global_load_dword v67, v79, s[36:37] offset:1024
	global_load_dword v68, v79, s[36:37] offset:2048
	global_load_dword v69, v79, s[36:37] offset:3072
	s_add_u32 s36, s6, 0x6000
	s_addc_u32 s37, s7, 0
	global_load_dword v70, v79, s[36:37]
	global_load_dword v71, v79, s[36:37] offset:1024
	global_load_dword v72, v79, s[36:37] offset:2048
	global_load_dword v73, v79, s[36:37] offset:3072
	s_add_u32 s36, s6, 0x7000
	s_addc_u32 s37, s7, 0
	global_load_dword v74, v79, s[36:37]
	global_load_dword v75, v79, s[36:37] offset:1024
	global_load_dword v76, v79, s[36:37] offset:2048
	global_load_dword v77, v79, s[36:37] offset:3072
	s_waitcnt vmcnt(0)
	v_lshlrev_b32_e32 v14, 16, v14
	v_lshlrev_b32_e32 v15, 16, v15
	v_lshlrev_b32_e32 v16, 16, v16
	v_lshlrev_b32_e32 v17, 16, v17
	v_lshlrev_b32_e32 v18, 16, v18
	v_lshlrev_b32_e32 v19, 16, v19
	v_lshlrev_b32_e32 v20, 16, v20
	v_lshlrev_b32_e32 v21, 16, v21
	v_lshlrev_b32_e32 v22, 16, v22
	v_lshlrev_b32_e32 v23, 16, v23
	v_lshlrev_b32_e32 v24, 16, v24
	v_lshlrev_b32_e32 v25, 16, v25
	v_lshlrev_b32_e32 v26, 16, v26
	v_lshlrev_b32_e32 v27, 16, v27
	v_lshlrev_b32_e32 v28, 16, v28
	v_lshlrev_b32_e32 v29, 16, v29
	v_lshlrev_b32_e32 v30, 16, v30
	v_lshlrev_b32_e32 v31, 16, v31
	v_lshlrev_b32_e32 v32, 16, v32
	v_lshlrev_b32_e32 v33, 16, v33
	v_lshlrev_b32_e32 v34, 16, v34
	v_lshlrev_b32_e32 v35, 16, v35
	v_lshlrev_b32_e32 v36, 16, v36
	v_lshlrev_b32_e32 v37, 16, v37
	v_lshlrev_b32_e32 v38, 16, v38
	v_lshlrev_b32_e32 v39, 16, v39
	v_lshlrev_b32_e32 v40, 16, v40
	v_lshlrev_b32_e32 v41, 16, v41
	v_lshlrev_b32_e32 v42, 16, v42
	v_lshlrev_b32_e32 v43, 16, v43
	v_lshlrev_b32_e32 v44, 16, v44
	v_lshlrev_b32_e32 v45, 16, v45
	v_fmac_f32_e32 v14, 0, v46
	v_fmac_f32_e32 v15, v47, v14
	v_mul_f32_e32 v47, v46, v47
	v_fmac_f32_e32 v16, v48, v15
	v_mul_f32_e32 v48, v47, v48
	v_fmac_f32_e32 v17, v49, v16
	v_mul_f32_e32 v49, v48, v49
	v_fmac_f32_e32 v18, v50, v17
	v_mul_f32_e32 v50, v49, v50
	v_fmac_f32_e32 v19, v51, v18
	v_mul_f32_e32 v51, v50, v51
	v_fmac_f32_e32 v20, v52, v19
	v_mul_f32_e32 v52, v51, v52
	v_fmac_f32_e32 v21, v53, v20
	v_mul_f32_e32 v53, v52, v53
	v_fmac_f32_e32 v22, v54, v21
	v_mul_f32_e32 v54, v53, v54
	v_fmac_f32_e32 v23, v55, v22
	v_mul_f32_e32 v55, v54, v55
	v_fmac_f32_e32 v24, v56, v23
	v_mul_f32_e32 v56, v55, v56
	v_fmac_f32_e32 v25, v57, v24
	v_mul_f32_e32 v57, v56, v57
	v_fmac_f32_e32 v26, v58, v25
	v_mul_f32_e32 v58, v57, v58
	v_fmac_f32_e32 v27, v59, v26
	v_mul_f32_e32 v59, v58, v59
	v_fmac_f32_e32 v28, v60, v27
	v_mul_f32_e32 v60, v59, v60
	v_fmac_f32_e32 v29, v61, v28
	v_mul_f32_e32 v61, v60, v61
	v_fmac_f32_e32 v30, v62, v29
	v_mul_f32_e32 v62, v61, v62
	v_fmac_f32_e32 v31, v63, v30
	v_mul_f32_e32 v63, v62, v63
	v_fmac_f32_e32 v32, v64, v31
	v_mul_f32_e32 v64, v63, v64
	v_fmac_f32_e32 v33, v65, v32
	v_mul_f32_e32 v65, v64, v65
	v_fmac_f32_e32 v34, v66, v33
	v_mul_f32_e32 v66, v65, v66
	v_fmac_f32_e32 v35, v67, v34
	v_mul_f32_e32 v67, v66, v67
	v_fmac_f32_e32 v36, v68, v35
	v_mul_f32_e32 v68, v67, v68
	v_fmac_f32_e32 v37, v69, v36
	v_mul_f32_e32 v69, v68, v69
	v_fmac_f32_e32 v38, v70, v37
	v_mul_f32_e32 v70, v69, v70
	v_fmac_f32_e32 v39, v71, v38
	v_mul_f32_e32 v71, v70, v71
	v_fmac_f32_e32 v40, v72, v39
	v_mul_f32_e32 v72, v71, v72
	v_fmac_f32_e32 v41, v73, v40
	v_mul_f32_e32 v73, v72, v73
	v_fmac_f32_e32 v42, v74, v41
	v_mul_f32_e32 v74, v73, v74
	v_fmac_f32_e32 v43, v75, v42
	v_mul_f32_e32 v75, v74, v75
	v_fmac_f32_e32 v44, v76, v43
	v_mul_f32_e32 v76, v75, v76
	v_fmac_f32_e32 v45, v77, v44
	v_mul_f32_e32 v77, v76, v77
	ds_write_b32 v11, v45
	ds_write_b32 v11, v77 offset:2048
	s_waitcnt lgkmcnt(0)
	s_barrier
	v_mov_b32_e32 v6, 0
	s_and_saveexec_b64 s[18:19], s[38:39]
	s_cbranch_execz .Lscan_q1
	ds_read2st64_b32 v[6:7], v12 offset1:8
	s_waitcnt lgkmcnt(0)
	v_fmac_f32_e32 v6, 0, v7
.Lscan_q1:
	s_or_b64 exec, exec, s[18:19]
	s_and_saveexec_b64 s[18:19], s[40:41]
	s_cbranch_execz .Lscan_q2
	ds_read2st64_b32 v[8:9], v12 offset0:2 offset1:10
	s_waitcnt lgkmcnt(0)
	v_fmac_f32_e32 v8, v6, v9
	v_mov_b32_e32 v6, v8
.Lscan_q2:
	s_or_b64 exec, exec, s[18:19]
	s_and_saveexec_b64 s[18:19], s[42:43]
	s_cbranch_execz .Lscan_q3
	ds_read2st64_b32 v[8:9], v12 offset0:4 offset1:12
	s_waitcnt lgkmcnt(0)
	v_fmac_f32_e32 v8, v6, v9
	v_mov_b32_e32 v6, v8
.Lscan_q3:
	s_or_b64 exec, exec, s[18:19]
	s_add_u32 s18, s15, s1
	s_addc_u32 s19, s22, 0
	v_add_f32_e32 v82, 0, v6
	v_cvt_pk_bf16_f32 v82, v82, v82
	global_store_short v78, v82, s[18:19]
	v_fmac_f32_e32 v14, v46, v6
	v_cvt_pk_bf16_f32 v82, v14, v14
	s_add_u32 s36, s18, 0x10000
	s_addc_u32 s37, s19, 0
	global_store_short v78, v82, s[36:37]
	v_fmac_f32_e32 v15, v47, v6
	v_cvt_pk_bf16_f32 v82, v15, v15
	s_add_u32 s36, s18, 0x20000
	s_addc_u32 s37, s19, 0
	global_store_short v78, v82, s[36:37]
	v_fmac_f32_e32 v16, v48, v6
	v_cvt_pk_bf16_f32 v82, v16, v16
	s_add_u32 s36, s18, 0x30000
	s_addc_u32 s37, s19, 0
	global_store_short v78, v82, s[36:37]
	v_fmac_f32_e32 v17, v49, v6
	v_cvt_pk_bf16_f32 v82, v17, v17
	s_add_u32 s36, s18, 0x40000
	s_addc_u32 s37, s19, 0
	global_store_short v78, v82, s[36:37]
	v_fmac_f32_e32 v18, v50, v6
	v_cvt_pk_bf16_f32 v82, v18, v18
	s_add_u32 s36, s18, 0x50000
	s_addc_u32 s37, s19, 0
	global_store_short v78, v82, s[36:37]
	v_fmac_f32_e32 v19, v51, v6
	v_cvt_pk_bf16_f32 v82, v19, v19
	s_add_u32 s36, s18, 0x60000
	s_addc_u32 s37, s19, 0
	global_store_short v78, v82, s[36:37]
	v_fmac_f32_e32 v20, v52, v6
	v_cvt_pk_bf16_f32 v82, v20, v20
	s_add_u32 s36, s18, 0x70000
	s_addc_u32 s37, s19, 0
	global_store_short v78, v82, s[36:37]
	v_fmac_f32_e32 v21, v53, v6
	v_cvt_pk_bf16_f32 v82, v21, v21
	s_add_u32 s36, s18, 0x80000
	s_addc_u32 s37, s19, 0
	global_store_short v78, v82, s[36:37]
	v_fmac_f32_e32 v22, v54, v6
	v_cvt_pk_bf16_f32 v82, v22, v22
	s_add_u32 s36, s18, 0x90000
	s_addc_u32 s37, s19, 0
	global_store_short v78, v82, s[36:37]
	v_fmac_f32_e32 v23, v55, v6
	v_cvt_pk_bf16_f32 v82, v23, v23
	s_add_u32 s36, s18, 0xa0000
	s_addc_u32 s37, s19, 0
	global_store_short v78, v82, s[36:37]
	v_fmac_f32_e32 v24, v56, v6
	v_cvt_pk_bf16_f32 v82, v24, v24
	s_add_u32 s36, s18, 0xb0000
	s_addc_u32 s37, s19, 0
	global_store_short v78, v82, s[36:37]
	v_fmac_f32_e32 v25, v57, v6
	v_cvt_pk_bf16_f32 v82, v25, v25
	s_add_u32 s36, s18, 0xc0000
	s_addc_u32 s37, s19, 0
	global_store_short v78, v82, s[36:37]
	v_fmac_f32_e32 v26, v58, v6
	v_cvt_pk_bf16_f32 v82, v26, v26
	s_add_u32 s36, s18, 0xd0000
	s_addc_u32 s37, s19, 0
	global_store_short v78, v82, s[36:37]
	v_fmac_f32_e32 v27, v59, v6
	v_cvt_pk_bf16_f32 v82, v27, v27
	s_add_u32 s36, s18, 0xe0000
	s_addc_u32 s37, s19, 0
	global_store_short v78, v82, s[36:37]
	v_fmac_f32_e32 v28, v60, v6
	v_cvt_pk_bf16_f32 v82, v28, v28
	s_add_u32 s36, s18, 0xf0000
	s_addc_u32 s37, s19, 0
	global_store_short v78, v82, s[36:37]
	v_fmac_f32_e32 v29, v61, v6
	v_cvt_pk_bf16_f32 v82, v29, v29
	s_add_u32 s36, s18, 0x100000
	s_addc_u32 s37, s19, 0
	global_store_short v78, v82, s[36:37]
	v_fmac_f32_e32 v30, v62, v6
	v_cvt_pk_bf16_f32 v82, v30, v30
	s_add_u32 s36, s18, 0x110000
	s_addc_u32 s37, s19, 0
	global_store_short v78, v82, s[36:37]
	v_fmac_f32_e32 v31, v63, v6
	v_cvt_pk_bf16_f32 v82, v31, v31
	s_add_u32 s36, s18, 0x120000
	s_addc_u32 s37, s19, 0
	global_store_short v78, v82, s[36:37]
	v_fmac_f32_e32 v32, v64, v6
	v_cvt_pk_bf16_f32 v82, v32, v32
	s_add_u32 s36, s18, 0x130000
	s_addc_u32 s37, s19, 0
	global_store_short v78, v82, s[36:37]
	v_fmac_f32_e32 v33, v65, v6
	v_cvt_pk_bf16_f32 v82, v33, v33
	s_add_u32 s36, s18, 0x140000
	s_addc_u32 s37, s19, 0
	global_store_short v78, v82, s[36:37]
	v_fmac_f32_e32 v34, v66, v6
	v_cvt_pk_bf16_f32 v82, v34, v34
	s_add_u32 s36, s18, 0x150000
	s_addc_u32 s37, s19, 0
	global_store_short v78, v82, s[36:37]
	v_fmac_f32_e32 v35, v67, v6
	v_cvt_pk_bf16_f32 v82, v35, v35
	s_add_u32 s36, s18, 0x160000
	s_addc_u32 s37, s19, 0
	global_store_short v78, v82, s[36:37]
	v_fmac_f32_e32 v36, v68, v6
	v_cvt_pk_bf16_f32 v82, v36, v36
	s_add_u32 s36, s18, 0x170000
	s_addc_u32 s37, s19, 0
	global_store_short v78, v82, s[36:37]
	v_fmac_f32_e32 v37, v69, v6
	v_cvt_pk_bf16_f32 v82, v37, v37
	s_add_u32 s36, s18, 0x180000
	s_addc_u32 s37, s19, 0
	global_store_short v78, v82, s[36:37]
	v_fmac_f32_e32 v38, v70, v6
	v_cvt_pk_bf16_f32 v82, v38, v38
	s_add_u32 s36, s18, 0x190000
	s_addc_u32 s37, s19, 0
	global_store_short v78, v82, s[36:37]
	v_fmac_f32_e32 v39, v71, v6
	v_cvt_pk_bf16_f32 v82, v39, v39
	s_add_u32 s36, s18, 0x1a0000
	s_addc_u32 s37, s19, 0
	global_store_short v78, v82, s[36:37]
	v_fmac_f32_e32 v40, v72, v6
	v_cvt_pk_bf16_f32 v82, v40, v40
	s_add_u32 s36, s18, 0x1b0000
	s_addc_u32 s37, s19, 0
	global_store_short v78, v82, s[36:37]
	v_fmac_f32_e32 v41, v73, v6
	v_cvt_pk_bf16_f32 v82, v41, v41
	s_add_u32 s36, s18, 0x1c0000
	s_addc_u32 s37, s19, 0
	global_store_short v78, v82, s[36:37]
	v_fmac_f32_e32 v42, v74, v6
	v_cvt_pk_bf16_f32 v82, v42, v42
	s_add_u32 s36, s18, 0x1d0000
	s_addc_u32 s37, s19, 0
	global_store_short v78, v82, s[36:37]
	v_fmac_f32_e32 v43, v75, v6
	v_cvt_pk_bf16_f32 v82, v43, v43
	s_add_u32 s36, s18, 0x1e0000
	s_addc_u32 s37, s19, 0
	global_store_short v78, v82, s[36:37]
	v_fmac_f32_e32 v44, v76, v6
	v_cvt_pk_bf16_f32 v82, v44, v44
	s_add_u32 s36, s18, 0x1f0000
	s_addc_u32 s37, s19, 0
	global_store_short v78, v82, s[36:37]
	v_readlane_b32 s0, v236, 9
	s_add_i32 s24, s24, s0
	s_add_i32 s23, s23, s30
	s_cmpk_gt_i32 s24, 0xff
	s_barrier
	v_readlane_b32 s1, v236, 10
	s_cbranch_scc0 .LBB0_362
